# spatial-gating item: LDS B-fragment reads of K-steps 1..3 batched eight deep into free registers (fixed accumulators) instead of read-wait-MFMA per fragment
# speedup vs baseline: 1.0162x; 1.0162x over previous
.LBB0_714:
	s_or_b64 exec, exec, s[2:3]
	v_and_b32_e32 v63, 31, v55
	v_lshl_add_u32 v57, v63, 5, 0
	v_and_b32_e32 v50, 64, v217
	s_waitcnt lgkmcnt(0)
	s_barrier
	v_add_u32_e32 v69, 64, v50
	ds_read_b128 v[50:53], v57
	ds_read_b128 v[58:61], v57 offset:16
	v_lshlrev_b32_e32 v56, 2, v63
	v_ashrrev_i32_e32 v62, 5, v55
	v_cmp_ge_i32_e32 vcc, v62, v56
	s_movk_i32 s0, 0xffe8
	s_waitcnt vmcnt(7)
	v_cndmask_b32_e32 v65, 0, v46, vcc
	v_cmp_lt_i32_e32 vcc, v56, v62
	s_waitcnt lgkmcnt(1)
	v_mov_b32_e32 v46, v53
	v_cndmask_b32_e32 v64, 0, v47, vcc
	v_mov_b32_e32 v47, v51
	v_pk_mul_f32 v[46:47], v[64:65], v[46:47]
	s_nop 0
	v_and_b32_sdwa v51, v47, v221 dst_sel:DWORD dst_unused:UNUSED_PAD src0_sel:WORD_1 src1_sel:DWORD
	v_and_b32_sdwa v53, v46, v221 dst_sel:DWORD dst_unused:UNUSED_PAD src0_sel:WORD_1 src1_sel:DWORD
	v_add3_u32 v72, v47, v51, s23
	v_add3_u32 v46, v46, v53, s23
	v_or_b32_e32 v47, 3, v56
	v_and_b32_e32 v67, 0xffff0000, v46
	v_or_b32_e32 v46, 2, v56
	v_cmp_le_i32_e32 vcc, v47, v62
	v_and_b32_e32 v66, 0xffff0000, v72
	s_nop 0
	v_cndmask_b32_e32 v71, 0, v49, vcc
	v_cmp_le_i32_e32 vcc, v46, v62
	s_waitcnt lgkmcnt(0)
	v_mov_b32_e32 v49, v61
	v_cndmask_b32_e32 v70, 0, v48, vcc
	v_mov_b32_e32 v48, v59
	v_pk_mul_f32 v[48:49], v[70:71], v[48:49]
	s_nop 0
	v_and_b32_sdwa v51, v49, v221 dst_sel:DWORD dst_unused:UNUSED_PAD src0_sel:WORD_1 src1_sel:DWORD
	v_and_b32_sdwa v53, v48, v221 dst_sel:DWORD dst_unused:UNUSED_PAD src0_sel:WORD_1 src1_sel:DWORD
	v_add3_u32 v49, v49, v51, s23
	v_add3_u32 v73, v48, v53, s23
	v_mov_b32_e32 v51, v52
	v_mul_f32_e32 v48, v52, v67
	v_and_b32_e32 v74, 0xffff0000, v49
	v_pk_fma_f32 v[50:51], v[50:51], v[66:67], v[48:49] op_sel_hi:[1,1,0]
	v_and_b32_e32 v48, 0xffff0000, v73
	v_mov_b32_e32 v49, v64
	v_mul_f32_e32 v52, v58, v48
	v_mul_f32_e32 v58, v60, v74
	v_pk_add_f32 v[60:61], v[64:65], v[48:49]
	v_xor_b32_e32 v48, 1, v217
	v_cmp_lt_i32_e32 vcc, v48, v69
	v_mov_b32_e32 v51, v70
	v_mov_b32_e32 v53, v71
	v_cndmask_b32_e32 v48, v217, v48, vcc
	v_pk_add_f32 v[50:51], v[50:51], v[52:53]
	v_mov_b32_e32 v59, v61
	v_lshlrev_b32_e32 v49, 2, v48
	v_pk_add_f32 v[50:51], v[58:59], v[50:51]
	v_mov_b32_e32 v110, v50
	v_mov_b32_e32 v111, v51
	v_xor_b32_e32 v48, 2, v217
	v_cmp_lt_i32_e32 vcc, v48, v69
	v_or_b32_sdwa v64, v67, v72 dst_sel:DWORD dst_unused:UNUSED_PAD src0_sel:DWORD src1_sel:WORD_1
	v_or_b32_sdwa v65, v74, v73 dst_sel:DWORD dst_unused:UNUSED_PAD src0_sel:DWORD src1_sel:WORD_1
	v_cndmask_b32_e32 v48, v217, v48, vcc
	v_lshlrev_b32_e32 v58, 2, v48
	v_xor_b32_e32 v48, 4, v217
	v_cmp_lt_i32_e32 vcc, v48, v69
	v_cndmask_b32_e32 v48, v217, v48, vcc
	v_lshlrev_b32_e32 v59, 2, v48
	v_xor_b32_e32 v48, 8, v217
	v_cmp_lt_i32_e32 vcc, v48, v69
	v_cndmask_b32_e32 v48, v217, v48, vcc
	v_lshlrev_b32_e32 v60, 2, v48
	v_mad_i32_i24 v48, v63, s0, v57
	v_cmp_eq_u32_e32 vcc, 0, v63
	v_xor_b32_e32 v52, 16, v217
	v_cmp_lt_i32_e64 s[0:1], v52, v69
	s_nop 1
	v_cndmask_b32_e64 v52, v217, v52, s[0:1]
	v_lshlrev_b32_e32 v61, 2, v52
	v_mad_u64_u32 v[66:67], s[0:1], v62, s13, v[48:49]
	ds_write_b64 v66, v[64:65] offset:2048
	v_add_u32_e32 v50, 0x200, v55
	ds_read_b128 v[62:65], v57
	ds_read_b128 v[70:73], v57 offset:16
	v_ashrrev_i32_e32 v50, 5, v50
	v_cmp_ge_i32_e64 s[0:1], v50, v46
	s_waitcnt lgkmcnt(1)
	v_mov_b32_e32 v66, v63
	s_waitcnt vmcnt(6)
	v_cndmask_b32_e64 v53, 0, v44, s[0:1]
	v_cmp_lt_i32_e64 s[0:1], v56, v50
	v_mov_b32_e32 v44, v65
	s_waitcnt lgkmcnt(0)
	v_mov_b32_e32 v67, v73
	v_cndmask_b32_e64 v52, 0, v43, s[0:1]
	v_cmp_le_i32_e64 s[0:1], v47, v50
	s_nop 1
	v_cndmask_b32_e64 v43, 0, v45, s[0:1]
	v_mov_b32_e32 v45, v71
	v_cmp_le_i32_e64 s[0:1], v56, v50
	v_pk_mul_f32 v[44:45], v[52:53], v[44:45]
	s_nop 0
	v_cndmask_b32_e64 v42, 0, v42, s[0:1]
	v_and_b32_sdwa v63, v44, v221 dst_sel:DWORD dst_unused:UNUSED_PAD src0_sel:WORD_1 src1_sel:DWORD
	v_pk_mul_f32 v[66:67], v[42:43], v[66:67]
	v_and_b32_sdwa v51, v45, v221 dst_sel:DWORD dst_unused:UNUSED_PAD src0_sel:WORD_1 src1_sel:DWORD
	v_add3_u32 v44, v44, v63, s23
	v_add3_u32 v51, v45, v51, s23
	v_and_b32_e32 v75, 0xffff0000, v44
	v_and_b32_sdwa v44, v67, v221 dst_sel:DWORD dst_unused:UNUSED_PAD src0_sel:WORD_1 src1_sel:DWORD
	v_and_b32_sdwa v45, v66, v221 dst_sel:DWORD dst_unused:UNUSED_PAD src0_sel:WORD_1 src1_sel:DWORD
	v_add3_u32 v44, v67, v44, s23
	v_add3_u32 v69, v66, v45, s23
	v_and_b32_e32 v71, 0xffff0000, v44
	v_and_b32_e32 v74, 0xffff0000, v69
	v_mov_b32_e32 v63, v64
	v_mul_f32_e32 v44, v64, v75
	v_pk_fma_f32 v[44:45], v[62:63], v[74:75], v[44:45] op_sel_hi:[1,1,0]
	v_pk_add_f32 v[66:67], v[42:43], v[52:53]
	v_and_b32_e32 v45, 0xffff0000, v51
	v_mul_f32_e32 v62, v70, v45
	v_mov_b32_e32 v45, v53
	v_mov_b32_e32 v63, v43
	v_mul_f32_e32 v64, v72, v71
	v_pk_add_f32 v[42:43], v[44:45], v[62:63]
	v_mov_b32_e32 v65, v66
	v_pk_add_f32 v[42:43], v[64:65], v[42:43]
	v_mov_b32_e32 v112, v42
	v_mov_b32_e32 v113, v43
	v_or_b32_sdwa v53, v71, v51 dst_sel:DWORD dst_unused:UNUSED_PAD src0_sel:DWORD src1_sel:WORD_1
	v_or_b32_sdwa v52, v69, v75 dst_sel:DWORD dst_unused:UNUSED_PAD src0_sel:WORD_1 src1_sel:DWORD
	v_mad_u64_u32 v[62:63], s[0:1], v50, s13, v[48:49]
	ds_write_b64 v62, v[52:53] offset:2048
	v_add_u32_e32 v42, 0x400, v55
	ds_read_b128 v[50:53], v57
	ds_read_b128 v[62:65], v57 offset:16
	v_ashrrev_i32_e32 v42, 5, v42
	v_cmp_ge_i32_e64 s[0:1], v42, v46
	s_waitcnt lgkmcnt(1)
	v_mov_b32_e32 v66, v51
	s_waitcnt vmcnt(5)
	v_cndmask_b32_e64 v45, 0, v40, s[0:1]
	v_cmp_lt_i32_e64 s[0:1], v56, v42
	v_mov_b32_e32 v40, v53
	s_waitcnt lgkmcnt(0)
	v_mov_b32_e32 v67, v65
	v_cndmask_b32_e64 v44, 0, v39, s[0:1]
	v_cmp_le_i32_e64 s[0:1], v47, v42
	s_nop 1
	v_cndmask_b32_e64 v39, 0, v41, s[0:1]
	v_mov_b32_e32 v41, v63
	v_cmp_le_i32_e64 s[0:1], v56, v42
	v_pk_mul_f32 v[40:41], v[44:45], v[40:41]
	s_nop 0
	v_cndmask_b32_e64 v38, 0, v38, s[0:1]
	v_and_b32_sdwa v51, v40, v221 dst_sel:DWORD dst_unused:UNUSED_PAD src0_sel:WORD_1 src1_sel:DWORD
	v_pk_mul_f32 v[66:67], v[38:39], v[66:67]
	v_and_b32_sdwa v43, v41, v221 dst_sel:DWORD dst_unused:UNUSED_PAD src0_sel:WORD_1 src1_sel:DWORD
	v_add3_u32 v40, v40, v51, s23
	v_add3_u32 v43, v41, v43, s23
	v_and_b32_e32 v71, 0xffff0000, v40
	v_and_b32_sdwa v40, v67, v221 dst_sel:DWORD dst_unused:UNUSED_PAD src0_sel:WORD_1 src1_sel:DWORD
	v_and_b32_sdwa v41, v66, v221 dst_sel:DWORD dst_unused:UNUSED_PAD src0_sel:WORD_1 src1_sel:DWORD
	v_add3_u32 v40, v67, v40, s23
	v_add3_u32 v65, v66, v41, s23
	v_and_b32_e32 v66, 0xffff0000, v40
	v_and_b32_e32 v70, 0xffff0000, v65
	v_mov_b32_e32 v51, v52
	v_mul_f32_e32 v40, v52, v71
	v_pk_fma_f32 v[40:41], v[50:51], v[70:71], v[40:41] op_sel_hi:[1,1,0]
	v_mov_b32_e32 v51, v39
	v_and_b32_e32 v41, 0xffff0000, v43
	v_mul_f32_e32 v50, v62, v41
	v_pk_add_f32 v[62:63], v[38:39], v[44:45]
	v_mov_b32_e32 v41, v45
	v_mul_f32_e32 v52, v64, v66
	v_pk_add_f32 v[38:39], v[40:41], v[50:51]
	v_mov_b32_e32 v53, v62
	v_pk_add_f32 v[38:39], v[52:53], v[38:39]
	v_mov_b32_e32 v114, v38
	v_mov_b32_e32 v115, v39
	v_or_b32_sdwa v45, v66, v43 dst_sel:DWORD dst_unused:UNUSED_PAD src0_sel:DWORD src1_sel:WORD_1
	v_or_b32_sdwa v44, v65, v71 dst_sel:DWORD dst_unused:UNUSED_PAD src0_sel:WORD_1 src1_sel:DWORD
	v_mad_u64_u32 v[50:51], s[0:1], v42, s13, v[48:49]
	ds_write_b64 v50, v[44:45] offset:2048
	v_add_u32_e32 v38, 0x600, v55
	s_waitcnt lgkmcnt(0)
	ds_read_b128 v[40:43], v57
	ds_read_b128 v[50:53], v57 offset:16
	v_ashrrev_i32_e32 v38, 5, v38
	v_cmp_ge_i32_e64 s[0:1], v38, v46
	s_waitcnt lgkmcnt(1)
	v_mov_b32_e32 v62, v41
	s_waitcnt vmcnt(4)
	v_cndmask_b32_e64 v45, 0, v36, s[0:1]
	v_cmp_lt_i32_e64 s[0:1], v56, v38
	v_mov_b32_e32 v36, v43
	s_waitcnt lgkmcnt(0)
	v_mov_b32_e32 v63, v53
	v_cndmask_b32_e64 v44, 0, v35, s[0:1]
	v_cmp_le_i32_e64 s[0:1], v47, v38
	s_nop 1
	v_cndmask_b32_e64 v35, 0, v37, s[0:1]
	v_mov_b32_e32 v37, v51
	v_cmp_le_i32_e64 s[0:1], v56, v38
	v_pk_mul_f32 v[36:37], v[44:45], v[36:37]
	s_nop 0
	v_cndmask_b32_e64 v34, 0, v34, s[0:1]
	v_and_b32_sdwa v41, v36, v221 dst_sel:DWORD dst_unused:UNUSED_PAD src0_sel:WORD_1 src1_sel:DWORD
	v_pk_mul_f32 v[62:63], v[34:35], v[62:63]
	v_and_b32_sdwa v39, v37, v221 dst_sel:DWORD dst_unused:UNUSED_PAD src0_sel:WORD_1 src1_sel:DWORD
	v_add3_u32 v36, v36, v41, s23
	v_add3_u32 v39, v37, v39, s23
	v_and_b32_e32 v65, 0xffff0000, v36
	v_and_b32_sdwa v36, v63, v221 dst_sel:DWORD dst_unused:UNUSED_PAD src0_sel:WORD_1 src1_sel:DWORD
	v_and_b32_sdwa v37, v62, v221 dst_sel:DWORD dst_unused:UNUSED_PAD src0_sel:WORD_1 src1_sel:DWORD
	v_add3_u32 v36, v63, v36, s23
	v_add3_u32 v53, v62, v37, s23
	v_and_b32_e32 v62, 0xffff0000, v36
	v_and_b32_e32 v64, 0xffff0000, v53
	v_mov_b32_e32 v41, v42
	v_mul_f32_e32 v36, v42, v65
	v_pk_fma_f32 v[36:37], v[40:41], v[64:65], v[36:37] op_sel_hi:[1,1,0]
	v_mov_b32_e32 v41, v35
	v_and_b32_e32 v37, 0xffff0000, v39
	v_mul_f32_e32 v40, v50, v37
	v_pk_add_f32 v[50:51], v[34:35], v[44:45]
	v_mov_b32_e32 v37, v45
	v_mul_f32_e32 v42, v52, v62
	v_pk_add_f32 v[34:35], v[36:37], v[40:41]
	v_mov_b32_e32 v43, v50
	v_pk_add_f32 v[34:35], v[42:43], v[34:35]
	v_mov_b32_e32 v116, v34
	v_mov_b32_e32 v117, v35
	v_or_b32_sdwa v41, v62, v39 dst_sel:DWORD dst_unused:UNUSED_PAD src0_sel:DWORD src1_sel:WORD_1
	v_or_b32_sdwa v40, v53, v65 dst_sel:DWORD dst_unused:UNUSED_PAD src0_sel:WORD_1 src1_sel:DWORD
	v_mad_u64_u32 v[42:43], s[0:1], v38, s13, v[48:49]
	ds_write_b64 v42, v[40:41] offset:2048
	v_add_u32_e32 v34, 0x800, v55
	s_waitcnt lgkmcnt(0)
	ds_read_b128 v[36:39], v57
	ds_read_b128 v[40:43], v57 offset:16
	v_ashrrev_i32_e32 v34, 5, v34
	v_cmp_ge_i32_e64 s[0:1], v34, v46
	s_waitcnt lgkmcnt(1)
	v_mov_b32_e32 v50, v37
	s_waitcnt vmcnt(3)
	v_cndmask_b32_e64 v45, 0, v32, s[0:1]
	v_cmp_lt_i32_e64 s[0:1], v56, v34
	v_mov_b32_e32 v32, v39
	s_waitcnt lgkmcnt(0)
	v_mov_b32_e32 v51, v43
	v_cndmask_b32_e64 v44, 0, v31, s[0:1]
	v_cmp_le_i32_e64 s[0:1], v47, v34
	s_nop 1
	v_cndmask_b32_e64 v31, 0, v33, s[0:1]
	v_mov_b32_e32 v33, v41
	v_cmp_le_i32_e64 s[0:1], v56, v34
	v_pk_mul_f32 v[32:33], v[44:45], v[32:33]
	s_nop 0
	v_cndmask_b32_e64 v30, 0, v30, s[0:1]
	v_and_b32_sdwa v37, v32, v221 dst_sel:DWORD dst_unused:UNUSED_PAD src0_sel:WORD_1 src1_sel:DWORD
	v_pk_mul_f32 v[50:51], v[30:31], v[50:51]
	v_and_b32_sdwa v35, v33, v221 dst_sel:DWORD dst_unused:UNUSED_PAD src0_sel:WORD_1 src1_sel:DWORD
	v_add3_u32 v32, v32, v37, s23
	v_add3_u32 v35, v33, v35, s23
	v_and_b32_e32 v53, 0xffff0000, v32
	v_and_b32_sdwa v32, v51, v221 dst_sel:DWORD dst_unused:UNUSED_PAD src0_sel:WORD_1 src1_sel:DWORD
	v_and_b32_sdwa v33, v50, v221 dst_sel:DWORD dst_unused:UNUSED_PAD src0_sel:WORD_1 src1_sel:DWORD
	v_add3_u32 v32, v51, v32, s23
	v_add3_u32 v43, v50, v33, s23
	v_and_b32_e32 v50, 0xffff0000, v32
	v_and_b32_e32 v52, 0xffff0000, v43
	v_mov_b32_e32 v37, v38
	v_mul_f32_e32 v32, v38, v53
	v_pk_fma_f32 v[32:33], v[36:37], v[52:53], v[32:33] op_sel_hi:[1,1,0]
	v_mov_b32_e32 v37, v31
	v_and_b32_e32 v33, 0xffff0000, v35
	v_mul_f32_e32 v36, v40, v33
	v_pk_add_f32 v[40:41], v[30:31], v[44:45]
	v_mov_b32_e32 v33, v45
	v_mul_f32_e32 v38, v42, v50
	v_pk_add_f32 v[30:31], v[32:33], v[36:37]
	v_mov_b32_e32 v39, v40
	v_pk_add_f32 v[30:31], v[38:39], v[30:31]
	v_mov_b32_e32 v118, v30
	v_mov_b32_e32 v119, v31
	v_or_b32_sdwa v37, v50, v35 dst_sel:DWORD dst_unused:UNUSED_PAD src0_sel:DWORD src1_sel:WORD_1
	v_or_b32_sdwa v36, v43, v53 dst_sel:DWORD dst_unused:UNUSED_PAD src0_sel:WORD_1 src1_sel:DWORD
	v_mad_u64_u32 v[38:39], s[0:1], v34, s13, v[48:49]
	ds_write_b64 v38, v[36:37] offset:2048
	v_add_u32_e32 v30, 0xa00, v55
	s_waitcnt lgkmcnt(0)
	ds_read_b128 v[32:35], v57
	ds_read_b128 v[36:39], v57 offset:16
	v_ashrrev_i32_e32 v30, 5, v30
	v_cmp_ge_i32_e64 s[0:1], v30, v46
	s_waitcnt lgkmcnt(1)
	v_mov_b32_e32 v42, v33
	s_waitcnt vmcnt(2)
	v_cndmask_b32_e64 v41, 0, v28, s[0:1]
	v_cmp_lt_i32_e64 s[0:1], v56, v30
	v_mov_b32_e32 v28, v35
	s_waitcnt lgkmcnt(0)
	v_mov_b32_e32 v43, v39
	v_cndmask_b32_e64 v40, 0, v27, s[0:1]
	v_cmp_le_i32_e64 s[0:1], v47, v30
	s_nop 1
	v_cndmask_b32_e64 v27, 0, v29, s[0:1]
	v_mov_b32_e32 v29, v37
	v_cmp_le_i32_e64 s[0:1], v56, v30
	v_pk_mul_f32 v[28:29], v[40:41], v[28:29]
	s_nop 0
	v_cndmask_b32_e64 v26, 0, v26, s[0:1]
	v_and_b32_sdwa v33, v28, v221 dst_sel:DWORD dst_unused:UNUSED_PAD src0_sel:WORD_1 src1_sel:DWORD
	v_pk_mul_f32 v[42:43], v[26:27], v[42:43]
	v_and_b32_sdwa v31, v29, v221 dst_sel:DWORD dst_unused:UNUSED_PAD src0_sel:WORD_1 src1_sel:DWORD
	v_add3_u32 v28, v28, v33, s23
	v_add3_u32 v31, v29, v31, s23
	v_and_b32_e32 v45, 0xffff0000, v28
	v_and_b32_sdwa v28, v43, v221 dst_sel:DWORD dst_unused:UNUSED_PAD src0_sel:WORD_1 src1_sel:DWORD
	v_and_b32_sdwa v29, v42, v221 dst_sel:DWORD dst_unused:UNUSED_PAD src0_sel:WORD_1 src1_sel:DWORD
	v_add3_u32 v28, v43, v28, s23
	v_add3_u32 v39, v42, v29, s23
	v_and_b32_e32 v42, 0xffff0000, v28
	v_and_b32_e32 v44, 0xffff0000, v39
	v_mov_b32_e32 v33, v34
	v_mul_f32_e32 v28, v34, v45
	v_pk_fma_f32 v[28:29], v[32:33], v[44:45], v[28:29] op_sel_hi:[1,1,0]
	v_mov_b32_e32 v33, v27
	v_and_b32_e32 v29, 0xffff0000, v31
	v_mul_f32_e32 v32, v36, v29
	v_pk_add_f32 v[36:37], v[26:27], v[40:41]
	v_mov_b32_e32 v29, v41
	v_mul_f32_e32 v34, v38, v42
	v_pk_add_f32 v[26:27], v[28:29], v[32:33]
	v_mov_b32_e32 v35, v36
	v_pk_add_f32 v[26:27], v[34:35], v[26:27]
	v_mov_b32_e32 v120, v26
	v_mov_b32_e32 v121, v27
	v_or_b32_sdwa v33, v42, v31 dst_sel:DWORD dst_unused:UNUSED_PAD src0_sel:DWORD src1_sel:WORD_1
	v_or_b32_sdwa v32, v39, v45 dst_sel:DWORD dst_unused:UNUSED_PAD src0_sel:WORD_1 src1_sel:DWORD
	v_mad_u64_u32 v[34:35], s[0:1], v30, s13, v[48:49]
	ds_write_b64 v34, v[32:33] offset:2048
	v_add_u32_e32 v26, 0xc00, v55
	s_waitcnt lgkmcnt(0)
	ds_read_b128 v[28:31], v57
	ds_read_b128 v[32:35], v57 offset:16
	v_ashrrev_i32_e32 v26, 5, v26
	v_cmp_ge_i32_e64 s[0:1], v26, v46
	s_waitcnt lgkmcnt(1)
	v_mov_b32_e32 v38, v29
	s_waitcnt vmcnt(1)
	v_cndmask_b32_e64 v37, 0, v24, s[0:1]
	v_cmp_lt_i32_e64 s[0:1], v56, v26
	v_mov_b32_e32 v24, v31
	s_waitcnt lgkmcnt(0)
	v_mov_b32_e32 v39, v35
	v_cndmask_b32_e64 v36, 0, v23, s[0:1]
	v_cmp_le_i32_e64 s[0:1], v47, v26
	s_nop 1
	v_cndmask_b32_e64 v23, 0, v25, s[0:1]
	v_mov_b32_e32 v25, v33
	v_cmp_le_i32_e64 s[0:1], v56, v26
	v_pk_mul_f32 v[24:25], v[36:37], v[24:25]
	s_nop 0
	v_cndmask_b32_e64 v22, 0, v22, s[0:1]
	v_and_b32_sdwa v29, v24, v221 dst_sel:DWORD dst_unused:UNUSED_PAD src0_sel:WORD_1 src1_sel:DWORD
	v_pk_mul_f32 v[38:39], v[22:23], v[38:39]
	v_and_b32_sdwa v27, v25, v221 dst_sel:DWORD dst_unused:UNUSED_PAD src0_sel:WORD_1 src1_sel:DWORD
	v_add3_u32 v24, v24, v29, s23
	v_add3_u32 v27, v25, v27, s23
	v_and_b32_e32 v41, 0xffff0000, v24
	v_and_b32_sdwa v24, v39, v221 dst_sel:DWORD dst_unused:UNUSED_PAD src0_sel:WORD_1 src1_sel:DWORD
	v_and_b32_sdwa v25, v38, v221 dst_sel:DWORD dst_unused:UNUSED_PAD src0_sel:WORD_1 src1_sel:DWORD
	v_add3_u32 v24, v39, v24, s23
	v_add3_u32 v35, v38, v25, s23
	v_and_b32_e32 v38, 0xffff0000, v24
	v_and_b32_e32 v40, 0xffff0000, v35
	v_mov_b32_e32 v29, v30
	v_mul_f32_e32 v24, v30, v41
	v_pk_fma_f32 v[24:25], v[28:29], v[40:41], v[24:25] op_sel_hi:[1,1,0]
	v_mov_b32_e32 v29, v23
	v_and_b32_e32 v25, 0xffff0000, v27
	v_mul_f32_e32 v28, v32, v25
	v_pk_add_f32 v[32:33], v[22:23], v[36:37]
	v_mov_b32_e32 v25, v37
	v_mul_f32_e32 v30, v34, v38
	v_pk_add_f32 v[22:23], v[24:25], v[28:29]
	v_mov_b32_e32 v31, v32
	v_pk_add_f32 v[22:23], v[30:31], v[22:23]
	v_mov_b32_e32 v122, v22
	v_mov_b32_e32 v123, v23
	v_or_b32_sdwa v29, v38, v27 dst_sel:DWORD dst_unused:UNUSED_PAD src0_sel:DWORD src1_sel:WORD_1
	v_or_b32_sdwa v28, v35, v41 dst_sel:DWORD dst_unused:UNUSED_PAD src0_sel:WORD_1 src1_sel:DWORD
	v_mad_u64_u32 v[30:31], s[0:1], v26, s13, v[48:49]
	ds_write_b64 v30, v[28:29] offset:2048
	v_add_u32_e32 v22, 0xe00, v55
	s_waitcnt lgkmcnt(0)
	ds_read_b128 v[24:27], v57
	ds_read_b128 v[28:31], v57 offset:16
	v_ashrrev_i32_e32 v22, 5, v22
	v_cmp_ge_i32_e64 s[0:1], v22, v46
	s_waitcnt lgkmcnt(1)
	v_mov_b32_e32 v34, v25
	s_waitcnt vmcnt(0)
	v_cndmask_b32_e64 v33, 0, v20, s[0:1]
	v_cmp_lt_i32_e64 s[0:1], v56, v22
	v_mov_b32_e32 v20, v27
	s_waitcnt lgkmcnt(0)
	v_mov_b32_e32 v35, v31
	v_cndmask_b32_e64 v32, 0, v19, s[0:1]
	v_cmp_le_i32_e64 s[0:1], v47, v22
	s_nop 1
	v_cndmask_b32_e64 v19, 0, v21, s[0:1]
	v_mov_b32_e32 v21, v29
	v_cmp_le_i32_e64 s[0:1], v56, v22
	v_pk_mul_f32 v[20:21], v[32:33], v[20:21]
	s_nop 0
	v_cndmask_b32_e64 v18, 0, v18, s[0:1]
	v_and_b32_sdwa v25, v20, v221 dst_sel:DWORD dst_unused:UNUSED_PAD src0_sel:WORD_1 src1_sel:DWORD
	v_pk_mul_f32 v[34:35], v[18:19], v[34:35]
	v_and_b32_sdwa v23, v21, v221 dst_sel:DWORD dst_unused:UNUSED_PAD src0_sel:WORD_1 src1_sel:DWORD
	v_add3_u32 v20, v20, v25, s23
	v_add3_u32 v23, v21, v23, s23
	v_and_b32_e32 v37, 0xffff0000, v20
	v_and_b32_sdwa v20, v35, v221 dst_sel:DWORD dst_unused:UNUSED_PAD src0_sel:WORD_1 src1_sel:DWORD
	v_and_b32_sdwa v21, v34, v221 dst_sel:DWORD dst_unused:UNUSED_PAD src0_sel:WORD_1 src1_sel:DWORD
	v_add3_u32 v20, v35, v20, s23
	v_add3_u32 v31, v34, v21, s23
	v_and_b32_e32 v34, 0xffff0000, v20
	v_and_b32_e32 v36, 0xffff0000, v31
	v_mov_b32_e32 v25, v26
	v_mul_f32_e32 v20, v26, v37
	v_pk_fma_f32 v[20:21], v[24:25], v[36:37], v[20:21] op_sel_hi:[1,1,0]
	v_mov_b32_e32 v25, v19
	v_and_b32_e32 v21, 0xffff0000, v23
	v_mul_f32_e32 v24, v28, v21
	v_pk_add_f32 v[28:29], v[18:19], v[32:33]
	v_mov_b32_e32 v21, v33
	v_mul_f32_e32 v26, v30, v34
	v_pk_add_f32 v[18:19], v[20:21], v[24:25]
	v_mov_b32_e32 v27, v28
	v_pk_add_f32 v[18:19], v[26:27], v[18:19]
	v_mov_b32_e32 v124, v18
	v_mov_b32_e32 v125, v19
	v_or_b32_sdwa v25, v34, v23 dst_sel:DWORD dst_unused:UNUSED_PAD src0_sel:DWORD src1_sel:WORD_1
	v_or_b32_sdwa v24, v31, v37 dst_sel:DWORD dst_unused:UNUSED_PAD src0_sel:WORD_1 src1_sel:DWORD
	v_mad_u64_u32 v[26:27], s[0:1], v22, s13, v[48:49]
	ds_write_b64 v26, v[24:25] offset:2048
	ds_bpermute_b32 v126, v49, v110
	ds_bpermute_b32 v127, v49, v111
	ds_bpermute_b32 v128, v49, v112
	ds_bpermute_b32 v129, v49, v113
	ds_bpermute_b32 v130, v49, v114
	ds_bpermute_b32 v131, v49, v115
	ds_bpermute_b32 v132, v49, v116
	ds_bpermute_b32 v133, v49, v117
	s_waitcnt lgkmcnt(0)
	v_pk_add_f32 v[110:111], v[110:111], v[126:127]
	v_pk_add_f32 v[112:113], v[112:113], v[128:129]
	v_pk_add_f32 v[114:115], v[114:115], v[130:131]
	v_pk_add_f32 v[116:117], v[116:117], v[132:133]
	ds_bpermute_b32 v134, v49, v118
	ds_bpermute_b32 v135, v49, v119
	ds_bpermute_b32 v136, v49, v120
	ds_bpermute_b32 v137, v49, v121
	ds_bpermute_b32 v138, v49, v122
	ds_bpermute_b32 v139, v49, v123
	ds_bpermute_b32 v140, v49, v124
	ds_bpermute_b32 v141, v49, v125
	s_waitcnt lgkmcnt(0)
	v_pk_add_f32 v[118:119], v[118:119], v[134:135]
	v_pk_add_f32 v[120:121], v[120:121], v[136:137]
	v_pk_add_f32 v[122:123], v[122:123], v[138:139]
	v_pk_add_f32 v[124:125], v[124:125], v[140:141]
	ds_bpermute_b32 v126, v58, v110
	ds_bpermute_b32 v127, v58, v111
	ds_bpermute_b32 v128, v58, v112
	ds_bpermute_b32 v129, v58, v113
	ds_bpermute_b32 v130, v58, v114
	ds_bpermute_b32 v131, v58, v115
	ds_bpermute_b32 v132, v58, v116
	ds_bpermute_b32 v133, v58, v117
	s_waitcnt lgkmcnt(0)
	v_pk_add_f32 v[110:111], v[110:111], v[126:127]
	v_pk_add_f32 v[112:113], v[112:113], v[128:129]
	v_pk_add_f32 v[114:115], v[114:115], v[130:131]
	v_pk_add_f32 v[116:117], v[116:117], v[132:133]
	ds_bpermute_b32 v134, v58, v118
	ds_bpermute_b32 v135, v58, v119
	ds_bpermute_b32 v136, v58, v120
	ds_bpermute_b32 v137, v58, v121
	ds_bpermute_b32 v138, v58, v122
	ds_bpermute_b32 v139, v58, v123
	ds_bpermute_b32 v140, v58, v124
	ds_bpermute_b32 v141, v58, v125
	s_waitcnt lgkmcnt(0)
	v_pk_add_f32 v[118:119], v[118:119], v[134:135]
	v_pk_add_f32 v[120:121], v[120:121], v[136:137]
	v_pk_add_f32 v[122:123], v[122:123], v[138:139]
	v_pk_add_f32 v[124:125], v[124:125], v[140:141]
	ds_bpermute_b32 v126, v59, v110
	ds_bpermute_b32 v127, v59, v111
	ds_bpermute_b32 v128, v59, v112
	ds_bpermute_b32 v129, v59, v113
	ds_bpermute_b32 v130, v59, v114
	ds_bpermute_b32 v131, v59, v115
	ds_bpermute_b32 v132, v59, v116
	ds_bpermute_b32 v133, v59, v117
	s_waitcnt lgkmcnt(0)
	v_pk_add_f32 v[110:111], v[110:111], v[126:127]
	v_pk_add_f32 v[112:113], v[112:113], v[128:129]
	v_pk_add_f32 v[114:115], v[114:115], v[130:131]
	v_pk_add_f32 v[116:117], v[116:117], v[132:133]
	ds_bpermute_b32 v134, v59, v118
	ds_bpermute_b32 v135, v59, v119
	ds_bpermute_b32 v136, v59, v120
	ds_bpermute_b32 v137, v59, v121
	ds_bpermute_b32 v138, v59, v122
	ds_bpermute_b32 v139, v59, v123
	ds_bpermute_b32 v140, v59, v124
	ds_bpermute_b32 v141, v59, v125
	s_waitcnt lgkmcnt(0)
	v_pk_add_f32 v[118:119], v[118:119], v[134:135]
	v_pk_add_f32 v[120:121], v[120:121], v[136:137]
	v_pk_add_f32 v[122:123], v[122:123], v[138:139]
	v_pk_add_f32 v[124:125], v[124:125], v[140:141]
	ds_bpermute_b32 v126, v60, v110
	ds_bpermute_b32 v127, v60, v111
	ds_bpermute_b32 v128, v60, v112
	ds_bpermute_b32 v129, v60, v113
	ds_bpermute_b32 v130, v60, v114
	ds_bpermute_b32 v131, v60, v115
	ds_bpermute_b32 v132, v60, v116
	ds_bpermute_b32 v133, v60, v117
	s_waitcnt lgkmcnt(0)
	v_pk_add_f32 v[110:111], v[110:111], v[126:127]
	v_pk_add_f32 v[112:113], v[112:113], v[128:129]
	v_pk_add_f32 v[114:115], v[114:115], v[130:131]
	v_pk_add_f32 v[116:117], v[116:117], v[132:133]
	ds_bpermute_b32 v134, v60, v118
	ds_bpermute_b32 v135, v60, v119
	ds_bpermute_b32 v136, v60, v120
	ds_bpermute_b32 v137, v60, v121
	ds_bpermute_b32 v138, v60, v122
	ds_bpermute_b32 v139, v60, v123
	ds_bpermute_b32 v140, v60, v124
	ds_bpermute_b32 v141, v60, v125
	s_waitcnt lgkmcnt(0)
	v_pk_add_f32 v[118:119], v[118:119], v[134:135]
	v_pk_add_f32 v[120:121], v[120:121], v[136:137]
	v_pk_add_f32 v[122:123], v[122:123], v[138:139]
	v_pk_add_f32 v[124:125], v[124:125], v[140:141]
	ds_bpermute_b32 v126, v61, v110
	ds_bpermute_b32 v127, v61, v111
	ds_bpermute_b32 v128, v61, v112
	ds_bpermute_b32 v129, v61, v113
	ds_bpermute_b32 v130, v61, v114
	ds_bpermute_b32 v131, v61, v115
	ds_bpermute_b32 v132, v61, v116
	ds_bpermute_b32 v133, v61, v117
	s_waitcnt lgkmcnt(0)
	v_pk_add_f32 v[110:111], v[110:111], v[126:127]
	v_pk_add_f32 v[112:113], v[112:113], v[128:129]
	v_pk_add_f32 v[114:115], v[114:115], v[130:131]
	v_pk_add_f32 v[116:117], v[116:117], v[132:133]
	ds_bpermute_b32 v134, v61, v118
	ds_bpermute_b32 v135, v61, v119
	ds_bpermute_b32 v136, v61, v120
	ds_bpermute_b32 v137, v61, v121
	ds_bpermute_b32 v138, v61, v122
	ds_bpermute_b32 v139, v61, v123
	ds_bpermute_b32 v140, v61, v124
	ds_bpermute_b32 v141, v61, v125
	s_waitcnt lgkmcnt(0)
	v_pk_add_f32 v[118:119], v[118:119], v[134:135]
	v_pk_add_f32 v[120:121], v[120:121], v[136:137]
	v_pk_add_f32 v[122:123], v[122:123], v[138:139]
	v_pk_add_f32 v[124:125], v[124:125], v[140:141]
	v_lshrrev_b32_e32 v142, 5, v200
	v_lshlrev_b32_e32 v142, 3, v142
	s_and_saveexec_b64 s[0:1], vcc
	ds_write_b64 v142, v[110:111] offset:1024
	ds_write_b64 v142, v[112:113] offset:1152
	ds_write_b64 v142, v[114:115] offset:1280
	ds_write_b64 v142, v[116:117] offset:1408
	ds_write_b64 v142, v[118:119] offset:1536
	ds_write_b64 v142, v[120:121] offset:1664
	ds_write_b64 v142, v[122:123] offset:1792
	ds_write_b64 v142, v[124:125] offset:1920
	s_or_b64 exec, exec, s[0:1]
	s_add_i32 s12, s12, s7
	v_or_b32_e32 v72, s6, v68
	s_movk_i32 s0, 0x3500
	v_lshl_or_b32 v18, v54, 2, s12
	s_waitcnt lgkmcnt(1)
	v_mul_lo_u32 v20, v72, s0
	v_readlane_b32 s0, v252, 53
	v_ashrrev_i32_e32 v19, 31, v18
	s_waitcnt lgkmcnt(0)
	v_mov_b32_e32 v21, v1
	v_readlane_b32 s1, v252, 54
	v_lshlrev_b64 v[66:67], 1, v[18:19]
	v_readlane_b32 s40, v250, 6
	v_lshl_add_u64 v[20:21], v[20:21], 1, s[0:1]
	v_lshl_add_u64 v[20:21], v[20:21], 0, v[66:67]
	v_add_co_u32_e32 v22, vcc, 0x1000, v20
	s_lshl_b64 s[0:1], s[76:77], 9
	s_nop 0
	v_addc_co_u32_e32 v23, vcc, 0, v21, vcc
	global_load_dwordx2 v[62:63], v[22:23], off
	v_add_co_u32_e32 v22, vcc, 0x2000, v20
	v_readlane_b32 s41, v250, 7
	s_nop 0
	v_addc_co_u32_e32 v23, vcc, 0, v21, vcc
	global_load_dwordx2 v[64:65], v[22:23], off
	v_add_co_u32_e32 v22, vcc, 0x6b000, v20
	s_add_u32 s0, s40, s0
	s_nop 0
	v_addc_co_u32_e32 v23, vcc, 0, v21, vcc
	global_load_dwordx2 v[58:59], v[22:23], off
	v_add_co_u32_e32 v22, vcc, 0x6c000, v20
	v_mul_u32_u24_e32 v26, 0x110, v68
	s_nop 0
	v_addc_co_u32_e32 v23, vcc, 0, v21, vcc
	global_load_dwordx2 v[60:61], v[22:23], off
	v_add_co_u32_e32 v22, vcc, 0xd5000, v20
	s_addc_u32 s1, s41, s1
	s_nop 0
	v_addc_co_u32_e32 v23, vcc, 0, v21, vcc
	global_load_dwordx2 v[54:55], v[22:23], off
	v_add_co_u32_e32 v22, vcc, 0xd6000, v20
	v_add3_u32 v0, 0, v0, v26
	s_nop 0
	v_addc_co_u32_e32 v23, vcc, 0, v21, vcc
	global_load_dwordx2 v[56:57], v[22:23], off
	v_add_co_u32_e32 v22, vcc, 0x13f000, v20
	v_or_b32_e32 v106, 16, v68
	s_nop 0
	v_addc_co_u32_e32 v23, vcc, 0, v21, vcc
	global_load_dwordx2 v[50:51], v[22:23], off
	v_add_co_u32_e32 v22, vcc, 0x140000, v20
	v_or_b32_e32 v107, 32, v68
	s_nop 0
	v_addc_co_u32_e32 v23, vcc, 0, v21, vcc
	global_load_dwordx2 v[52:53], v[22:23], off
	v_add_co_u32_e32 v22, vcc, 0x1a9000, v20
	v_or_b32_e32 v108, 48, v68
	s_nop 0
	v_addc_co_u32_e32 v23, vcc, 0, v21, vcc
	global_load_dwordx2 v[46:47], v[22:23], off
	v_add_co_u32_e32 v22, vcc, 0x1aa000, v20
	v_or_b32_e32 v109, 64, v68
	s_nop 0
	v_addc_co_u32_e32 v23, vcc, 0, v21, vcc
	global_load_dwordx2 v[48:49], v[22:23], off
	v_add_co_u32_e32 v22, vcc, 0x213000, v20
	v_readlane_b32 s42, v250, 8
	s_nop 0
	v_addc_co_u32_e32 v23, vcc, 0, v21, vcc
	global_load_dwordx2 v[42:43], v[22:23], off
	v_add_co_u32_e32 v22, vcc, 0x214000, v20
	v_readlane_b32 s43, v250, 9
	s_nop 0
	v_addc_co_u32_e32 v23, vcc, 0, v21, vcc
	global_load_dwordx2 v[44:45], v[22:23], off
	v_add_co_u32_e32 v22, vcc, 0x27d000, v20
	s_nop 1
	v_addc_co_u32_e32 v23, vcc, 0, v21, vcc
	global_load_dwordx2 v[38:39], v[22:23], off
	v_add_co_u32_e32 v22, vcc, 0x27e000, v20
	s_nop 1
	v_addc_co_u32_e32 v23, vcc, 0, v21, vcc
	global_load_dwordx2 v[40:41], v[22:23], off
	v_add_co_u32_e32 v22, vcc, 0x2e7000, v20
	s_nop 1
	v_addc_co_u32_e32 v23, vcc, 0, v21, vcc
	v_add_co_u32_e32 v20, vcc, 0x2e8000, v20
	global_load_dwordx2 v[34:35], v[22:23], off
	s_nop 0
	v_addc_co_u32_e32 v21, vcc, 0, v21, vcc
	global_load_dwordx2 v[36:37], v[20:21], off
	v_lshlrev_b64 v[22:23], 2, v[18:19]
	v_lshlrev_b32_e32 v20, 2, v68
	v_lshl_add_u64 v[18:19], s[8:9], 0, v[22:23]
	v_lshl_add_u64 v[22:23], s[10:11], 0, v[22:23]
	global_load_dword v104, v20, s[0:1]
	global_load_dword v105, v20, s[0:1] offset:64
	global_load_dword v75, v20, s[0:1] offset:128
	global_load_dword v74, v20, s[0:1] offset:192
	global_load_dword v73, v20, s[0:1] offset:256
	global_load_dword v71, v20, s[0:1] offset:320
	global_load_dword v70, v20, s[0:1] offset:384
	global_load_dword v69, v20, s[0:1] offset:448
	v_readlane_b32 s0, v252, 55
	global_load_dwordx4 v[18:21], v[18:19], off
	v_readlane_b32 s1, v252, 56
	global_load_dwordx4 v[22:25], v[22:23], off
	s_barrier
	ds_read_b128 v[26:29], v0 offset:2048
	ds_read_b128 v[30:33], v0 offset:6400
	ds_read_b128 v[76:79], v0 offset:10752
	ds_read_b128 v[80:83], v0 offset:15104
	ds_read_b128 v[84:87], v0 offset:19456
	ds_read_b128 v[88:91], v0 offset:23808
	ds_read_b128 v[92:95], v0 offset:28160
	ds_read_b128 v[96:99], v0 offset:32512
	s_waitcnt lgkmcnt(7)
	v_mfma_f32_16x16x32_bf16 v[26:29], v[14:17], v[26:29], 0
	v_lshl_add_u64 v[66:67], s[0:1], 0, v[66:67]
	s_mov_b64 s[0:1], 0
	s_waitcnt lgkmcnt(6)
	v_mfma_f32_16x16x32_bf16 v[30:33], v[14:17], v[30:33], 0
	s_waitcnt lgkmcnt(5)
	v_mfma_f32_16x16x32_bf16 v[76:79], v[14:17], v[76:79], 0
	s_waitcnt lgkmcnt(4)
	v_mfma_f32_16x16x32_bf16 v[80:83], v[14:17], v[80:83], 0
	s_waitcnt lgkmcnt(3)
	v_mfma_f32_16x16x32_bf16 v[84:87], v[14:17], v[84:87], 0
	s_waitcnt lgkmcnt(2)
	v_mfma_f32_16x16x32_bf16 v[88:91], v[14:17], v[88:91], 0
	s_waitcnt lgkmcnt(1)
	v_mfma_f32_16x16x32_bf16 v[92:95], v[14:17], v[92:95], 0
	s_waitcnt lgkmcnt(0)
	v_mfma_f32_16x16x32_bf16 v[14:17], v[14:17], v[96:99], 0
	ds_read_b128 v[144:147], v0 offset:2112
	ds_read_b128 v[148:151], v0 offset:6464
	ds_read_b128 v[152:155], v0 offset:10816
	ds_read_b128 v[156:159], v0 offset:15168
	ds_read_b128 v[160:163], v0 offset:19520
	ds_read_b128 v[164:167], v0 offset:23872
	ds_read_b128 v[168:171], v0 offset:28224
	ds_read_b128 v[172:175], v0 offset:32576
	s_waitcnt lgkmcnt(7)
	v_mfma_f32_16x16x32_bf16 v[26:29], v[10:13], v[144:147], v[26:29]
	s_waitcnt lgkmcnt(6)
	v_mfma_f32_16x16x32_bf16 v[30:33], v[10:13], v[148:151], v[30:33]
	s_waitcnt lgkmcnt(5)
	v_mfma_f32_16x16x32_bf16 v[76:79], v[10:13], v[152:155], v[76:79]
	s_waitcnt lgkmcnt(4)
	v_mfma_f32_16x16x32_bf16 v[80:83], v[10:13], v[156:159], v[80:83]
	s_waitcnt lgkmcnt(3)
	v_mfma_f32_16x16x32_bf16 v[84:87], v[10:13], v[160:163], v[84:87]
	s_waitcnt lgkmcnt(2)
	v_mfma_f32_16x16x32_bf16 v[88:91], v[10:13], v[164:167], v[88:91]
	s_waitcnt lgkmcnt(1)
	v_mfma_f32_16x16x32_bf16 v[92:95], v[10:13], v[168:171], v[92:95]
	s_waitcnt lgkmcnt(0)
	v_mfma_f32_16x16x32_bf16 v[178:181], v[10:13], v[172:175], v[14:17]
	s_nop 7
	ds_read_b128 v[144:147], v0 offset:2176
	ds_read_b128 v[148:151], v0 offset:6528
	ds_read_b128 v[152:155], v0 offset:10880
	ds_read_b128 v[156:159], v0 offset:15232
	ds_read_b128 v[160:163], v0 offset:19584
	ds_read_b128 v[164:167], v0 offset:23936
	ds_read_b128 v[168:171], v0 offset:28288
	ds_read_b128 v[172:175], v0 offset:32640
	s_waitcnt lgkmcnt(7)
	v_mfma_f32_16x16x32_bf16 v[26:29], v[6:9], v[144:147], v[26:29]
	s_waitcnt lgkmcnt(6)
	v_mfma_f32_16x16x32_bf16 v[30:33], v[6:9], v[148:151], v[30:33]
	s_waitcnt lgkmcnt(5)
	v_mfma_f32_16x16x32_bf16 v[76:79], v[6:9], v[152:155], v[76:79]
	s_waitcnt lgkmcnt(4)
	v_mfma_f32_16x16x32_bf16 v[80:83], v[6:9], v[156:159], v[80:83]
	s_waitcnt lgkmcnt(3)
	v_mfma_f32_16x16x32_bf16 v[84:87], v[6:9], v[160:163], v[84:87]
	s_waitcnt lgkmcnt(2)
	v_mfma_f32_16x16x32_bf16 v[88:91], v[6:9], v[164:167], v[88:91]
	s_waitcnt lgkmcnt(1)
	v_mfma_f32_16x16x32_bf16 v[92:95], v[6:9], v[168:171], v[92:95]
	s_waitcnt lgkmcnt(0)
	v_mfma_f32_16x16x32_bf16 v[178:181], v[6:9], v[172:175], v[178:181]
	s_nop 7
	ds_read_b128 v[144:147], v0 offset:2240
	ds_read_b128 v[148:151], v0 offset:6592
	ds_read_b128 v[152:155], v0 offset:10944
	ds_read_b128 v[156:159], v0 offset:15296
	ds_read_b128 v[160:163], v0 offset:19648
	ds_read_b128 v[164:167], v0 offset:24000
	ds_read_b128 v[168:171], v0 offset:28352
	ds_read_b128 v[172:175], v0 offset:32704
	s_waitcnt lgkmcnt(7)
	v_mfma_f32_16x16x32_bf16 v[96:99], v[2:5], v[144:147], v[26:29]
	s_waitcnt lgkmcnt(6)
	v_mfma_f32_16x16x32_bf16 v[100:103], v[2:5], v[148:151], v[30:33]
	s_waitcnt lgkmcnt(5)
	v_mfma_f32_16x16x32_bf16 v[30:33], v[2:5], v[152:155], v[76:79]
	s_waitcnt lgkmcnt(4)
	v_mfma_f32_16x16x32_bf16 v[26:29], v[2:5], v[156:159], v[80:83]
	s_waitcnt lgkmcnt(3)
	v_mfma_f32_16x16x32_bf16 v[14:17], v[2:5], v[160:163], v[84:87]
	s_waitcnt lgkmcnt(2)
	v_mfma_f32_16x16x32_bf16 v[10:13], v[2:5], v[164:167], v[88:91]
	s_waitcnt lgkmcnt(1)
	v_mfma_f32_16x16x32_bf16 v[6:9], v[2:5], v[168:171], v[92:95]
	s_waitcnt lgkmcnt(0)
	v_mfma_f32_16x16x32_bf16 v[2:5], v[2:5], v[172:175], v[178:181]
	s_nop 15
	s_waitcnt lgkmcnt(0)
	s_waitcnt lgkmcnt(0)
	s_waitcnt lgkmcnt(0)
	s_waitcnt lgkmcnt(0)
	s_waitcnt lgkmcnt(0)
	s_waitcnt lgkmcnt(0)
	s_waitcnt lgkmcnt(0)
	s_waitcnt lgkmcnt(0)
	s_nop 2
	s_waitcnt lgkmcnt(0)
	s_nop 2
	s_waitcnt lgkmcnt(0)
	s_nop 2
	s_waitcnt lgkmcnt(0)
	s_nop 2
	s_waitcnt lgkmcnt(0)
	s_nop 2
	s_waitcnt lgkmcnt(0)
	s_nop 2
	s_waitcnt lgkmcnt(0)
	s_nop 2
	s_waitcnt lgkmcnt(0)
	s_nop 2
	s_waitcnt lgkmcnt(0)
	s_waitcnt lgkmcnt(0)
	s_waitcnt lgkmcnt(0)
	s_waitcnt lgkmcnt(0)
	s_waitcnt lgkmcnt(0)
	s_nop 1
	s_waitcnt lgkmcnt(0)
	s_nop 2
	v_lshl_add_u32 v0, v68, 3, 0
	s_waitcnt lgkmcnt(0)
	s_waitcnt lgkmcnt(0)
	ds_read_b64 v[76:77], v0 offset:1024
	s_waitcnt vmcnt(25)
	v_lshlrev_b32_e32 v0, 16, v62
	v_and_b32_e32 v62, 0xffff0000, v62
	v_or_b32_e32 v84, 0x50, v68
	v_or_b32_e32 v85, 0x60, v68
	s_waitcnt lgkmcnt(0)
	v_sub_f32_e32 v78, v96, v76
	s_waitcnt vmcnt(0)
	v_mul_f32_e32 v79, v22, v77
	v_fmac_f32_e32 v79, v18, v78
	v_add_f32_e32 v78, v104, v79
	v_mul_f32_e32 v0, v78, v0
	v_lshlrev_b32_e32 v78, 16, v64
	v_mul_f32_e32 v0, v0, v78
	v_sub_f32_e32 v78, v97, v76
	v_mul_f32_e32 v79, v23, v77
	v_fmac_f32_e32 v79, v19, v78
	v_add_f32_e32 v78, v104, v79
	v_mul_f32_e32 v62, v78, v62
	v_sub_f32_e32 v78, v98, v76
	v_mul_f32_e32 v79, v24, v77
	v_sub_f32_e32 v76, v99, v76
	v_mul_f32_e32 v77, v25, v77
	v_and_b32_e32 v64, 0xffff0000, v64
	v_fmac_f32_e32 v79, v20, v78
	v_fmac_f32_e32 v77, v21, v76
	v_mul_f32_e32 v62, v62, v64
	v_lshlrev_b32_e32 v64, 16, v63
	v_add_f32_e32 v78, v104, v79
	v_and_b32_e32 v63, 0xffff0000, v63
	v_add_f32_e32 v76, v104, v77
	v_mul_f32_e32 v64, v78, v64
	v_lshlrev_b32_e32 v78, 16, v65
	v_mul_f32_e32 v63, v76, v63
	v_and_b32_e32 v65, 0xffff0000, v65
	v_mul_f32_e32 v64, v64, v78
	v_mul_f32_e32 v63, v63, v65
	v_cvt_pk_bf16_f32 v62, v0, v62
	v_lshl_add_u32 v0, v106, 3, 0
	v_cvt_pk_bf16_f32 v63, v64, v63
	ds_read_b64 v[64:65], v0 offset:1024
	v_lshlrev_b32_e32 v0, 11, v72
	v_lshl_add_u64 v[76:77], v[66:67], 0, v[0:1]
	global_store_dwordx2 v[76:77], v[62:63], off
	v_lshlrev_b32_e32 v0, 16, v58
	s_waitcnt lgkmcnt(0)
	v_sub_f32_e32 v62, v100, v64
	v_mul_f32_e32 v63, v22, v65
	v_fmac_f32_e32 v63, v18, v62
	v_add_f32_e32 v62, v105, v63
	v_mul_f32_e32 v0, v62, v0
	v_lshlrev_b32_e32 v62, 16, v60
	v_mul_f32_e32 v0, v0, v62
	v_sub_f32_e32 v62, v101, v64
	v_mul_f32_e32 v63, v23, v65
	v_fmac_f32_e32 v63, v19, v62
	v_and_b32_e32 v58, 0xffff0000, v58
	v_add_f32_e32 v62, v105, v63
	v_mul_f32_e32 v58, v62, v58
	v_sub_f32_e32 v62, v102, v64
	v_mul_f32_e32 v63, v24, v65
	v_and_b32_e32 v60, 0xffff0000, v60
	v_fmac_f32_e32 v63, v20, v62
	v_mul_f32_e32 v58, v58, v60
	v_lshlrev_b32_e32 v60, 16, v59
	v_add_f32_e32 v62, v105, v63
	v_mul_f32_e32 v60, v62, v60
	v_lshlrev_b32_e32 v62, 16, v61
	v_mul_f32_e32 v60, v60, v62
	v_sub_f32_e32 v62, v103, v64
	v_mul_f32_e32 v63, v25, v65
	v_fmac_f32_e32 v63, v21, v62
	v_and_b32_e32 v59, 0xffff0000, v59
	v_add_f32_e32 v62, v105, v63
	v_mul_f32_e32 v59, v62, v59
	v_and_b32_e32 v61, 0xffff0000, v61
	v_mul_f32_e32 v59, v59, v61
	v_cvt_pk_bf16_f32 v58, v0, v58
	v_cvt_pk_bf16_f32 v59, v60, v59
	v_lshl_add_u32 v60, v107, 3, 0
	ds_read_b64 v[60:61], v60 offset:1024
	v_or_b32_e32 v0, s6, v106
	v_lshlrev_b32_e32 v0, 11, v0
	v_lshl_add_u64 v[62:63], v[66:67], 0, v[0:1]
	global_store_dwordx2 v[62:63], v[58:59], off
	s_waitcnt lgkmcnt(0)
	v_sub_f32_e32 v30, v30, v60
	v_mul_f32_e32 v58, v22, v61
	v_fmac_f32_e32 v58, v18, v30
	v_lshlrev_b32_e32 v0, 16, v54
	v_add_f32_e32 v30, v75, v58
	v_mul_f32_e32 v0, v30, v0
	v_lshlrev_b32_e32 v30, 16, v56
	v_mul_f32_e32 v0, v0, v30
	v_and_b32_e32 v30, 0xffff0000, v54
	v_sub_f32_e32 v31, v31, v60
	v_mul_f32_e32 v54, v23, v61
	v_fmac_f32_e32 v54, v19, v31
	v_add_f32_e32 v31, v75, v54
	v_sub_f32_e32 v32, v32, v60
	v_mul_f32_e32 v54, v24, v61
	v_mul_f32_e32 v30, v31, v30
	v_and_b32_e32 v31, 0xffff0000, v56
	v_fmac_f32_e32 v54, v20, v32
	v_mul_f32_e32 v30, v30, v31
	v_lshlrev_b32_e32 v31, 16, v55
	v_add_f32_e32 v32, v75, v54
	v_sub_f32_e32 v33, v33, v60
	v_mul_f32_e32 v54, v25, v61
	v_mul_f32_e32 v31, v32, v31
	v_lshlrev_b32_e32 v32, 16, v57
	v_fmac_f32_e32 v54, v21, v33
	v_mul_f32_e32 v31, v31, v32
	v_and_b32_e32 v32, 0xffff0000, v55
	v_add_f32_e32 v33, v75, v54
	v_mul_f32_e32 v32, v33, v32
	v_and_b32_e32 v33, 0xffff0000, v57
	v_mul_f32_e32 v32, v32, v33
	v_cvt_pk_bf16_f32 v30, v0, v30
	v_cvt_pk_bf16_f32 v31, v31, v32
	v_lshl_add_u32 v32, v108, 3, 0
	ds_read_b64 v[32:33], v32 offset:1024
	v_or_b32_e32 v0, s6, v107
	v_lshlrev_b32_e32 v0, 11, v0
	v_lshl_add_u64 v[54:55], v[66:67], 0, v[0:1]
	global_store_dwordx2 v[54:55], v[30:31], off
	s_waitcnt lgkmcnt(0)
	v_sub_f32_e32 v26, v26, v32
	v_mul_f32_e32 v30, v22, v33
	v_fmac_f32_e32 v30, v18, v26
	v_lshlrev_b32_e32 v0, 16, v50
	v_add_f32_e32 v26, v74, v30
	v_sub_f32_e32 v27, v27, v32
	v_mul_f32_e32 v30, v23, v33
	v_mul_f32_e32 v0, v26, v0
	v_lshlrev_b32_e32 v26, 16, v52
	v_fmac_f32_e32 v30, v19, v27
	v_mul_f32_e32 v0, v0, v26
	v_and_b32_e32 v26, 0xffff0000, v50
	v_add_f32_e32 v27, v74, v30
	v_sub_f32_e32 v28, v28, v32
	v_mul_f32_e32 v30, v24, v33
	v_mul_f32_e32 v26, v27, v26
	v_and_b32_e32 v27, 0xffff0000, v52
	v_fmac_f32_e32 v30, v20, v28
	v_mul_f32_e32 v26, v26, v27
	v_lshlrev_b32_e32 v27, 16, v51
	v_add_f32_e32 v28, v74, v30
	v_sub_f32_e32 v29, v29, v32
	v_mul_f32_e32 v30, v25, v33
	v_mul_f32_e32 v27, v28, v27
	v_lshlrev_b32_e32 v28, 16, v53
	v_fmac_f32_e32 v30, v21, v29
	v_mul_f32_e32 v27, v27, v28
	v_and_b32_e32 v28, 0xffff0000, v51
	v_add_f32_e32 v29, v74, v30
	v_mul_f32_e32 v28, v29, v28
	v_and_b32_e32 v29, 0xffff0000, v53
	v_mul_f32_e32 v28, v28, v29
	v_cvt_pk_bf16_f32 v26, v0, v26
	v_cvt_pk_bf16_f32 v27, v27, v28
	v_lshl_add_u32 v28, v109, 3, 0
	ds_read_b64 v[28:29], v28 offset:1024
	v_or_b32_e32 v0, s6, v108
	v_lshlrev_b32_e32 v0, 11, v0
	v_lshl_add_u64 v[30:31], v[66:67], 0, v[0:1]
	global_store_dwordx2 v[30:31], v[26:27], off
	s_waitcnt lgkmcnt(0)
	v_sub_f32_e32 v14, v14, v28
	v_mul_f32_e32 v26, v22, v29
	v_fmac_f32_e32 v26, v18, v14
	v_lshlrev_b32_e32 v0, 16, v46
	v_add_f32_e32 v14, v73, v26
	v_sub_f32_e32 v15, v15, v28
	v_mul_f32_e32 v26, v23, v29
	v_mul_f32_e32 v0, v14, v0
	v_lshlrev_b32_e32 v14, 16, v48
	v_fmac_f32_e32 v26, v19, v15
	v_mul_f32_e32 v0, v0, v14
	v_and_b32_e32 v14, 0xffff0000, v46
	v_add_f32_e32 v15, v73, v26
	v_sub_f32_e32 v16, v16, v28
	v_mul_f32_e32 v26, v24, v29
	v_mul_f32_e32 v14, v15, v14
	v_and_b32_e32 v15, 0xffff0000, v48
	v_fmac_f32_e32 v26, v20, v16
	v_mul_f32_e32 v14, v14, v15
	v_lshlrev_b32_e32 v15, 16, v47
	v_add_f32_e32 v16, v73, v26
	v_sub_f32_e32 v17, v17, v28
	v_mul_f32_e32 v26, v25, v29
	v_mul_f32_e32 v15, v16, v15
	v_lshlrev_b32_e32 v16, 16, v49
	v_fmac_f32_e32 v26, v21, v17
	v_mul_f32_e32 v15, v15, v16
	v_and_b32_e32 v16, 0xffff0000, v47
	v_add_f32_e32 v17, v73, v26
	v_mul_f32_e32 v16, v17, v16
	v_and_b32_e32 v17, 0xffff0000, v49
	v_mul_f32_e32 v16, v16, v17
	v_cvt_pk_bf16_f32 v14, v0, v14
	v_cvt_pk_bf16_f32 v15, v15, v16
	v_lshl_add_u32 v16, v84, 3, 0
	ds_read_b64 v[16:17], v16 offset:1024
	v_or_b32_e32 v0, s6, v109
	v_lshlrev_b32_e32 v0, 11, v0
	v_lshl_add_u64 v[26:27], v[66:67], 0, v[0:1]
	global_store_dwordx2 v[26:27], v[14:15], off
	s_waitcnt lgkmcnt(0)
	v_sub_f32_e32 v10, v10, v16
	v_mul_f32_e32 v14, v22, v17
	v_fmac_f32_e32 v14, v18, v10
	v_lshlrev_b32_e32 v0, 16, v42
	v_add_f32_e32 v10, v71, v14
	v_sub_f32_e32 v11, v11, v16
	v_mul_f32_e32 v14, v23, v17
	v_mul_f32_e32 v0, v10, v0
	v_lshlrev_b32_e32 v10, 16, v44
	v_fmac_f32_e32 v14, v19, v11
	v_mul_f32_e32 v0, v0, v10
	v_and_b32_e32 v10, 0xffff0000, v42
	v_add_f32_e32 v11, v71, v14
	v_sub_f32_e32 v12, v12, v16
	v_mul_f32_e32 v14, v24, v17
	v_mul_f32_e32 v10, v11, v10
	v_and_b32_e32 v11, 0xffff0000, v44
	v_fmac_f32_e32 v14, v20, v12
	v_mul_f32_e32 v10, v10, v11
	v_lshlrev_b32_e32 v11, 16, v43
	v_add_f32_e32 v12, v71, v14
	v_sub_f32_e32 v13, v13, v16
	v_mul_f32_e32 v14, v25, v17
	v_mul_f32_e32 v11, v12, v11
	v_lshlrev_b32_e32 v12, 16, v45
	v_fmac_f32_e32 v14, v21, v13
	v_mul_f32_e32 v11, v11, v12
	v_and_b32_e32 v12, 0xffff0000, v43
	v_add_f32_e32 v13, v71, v14
	v_mul_f32_e32 v12, v13, v12
	v_and_b32_e32 v13, 0xffff0000, v45
	v_mul_f32_e32 v12, v12, v13
	v_cvt_pk_bf16_f32 v10, v0, v10
	v_cvt_pk_bf16_f32 v11, v11, v12
	v_lshl_add_u32 v12, v85, 3, 0
	ds_read_b64 v[12:13], v12 offset:1024
	v_or_b32_e32 v0, s6, v84
	v_lshlrev_b32_e32 v0, 11, v0
	v_lshl_add_u64 v[14:15], v[66:67], 0, v[0:1]
	global_store_dwordx2 v[14:15], v[10:11], off
	s_waitcnt lgkmcnt(0)
	v_sub_f32_e32 v6, v6, v12
	v_mul_f32_e32 v10, v22, v13
	v_fmac_f32_e32 v10, v18, v6
	v_lshlrev_b32_e32 v0, 16, v38
	v_add_f32_e32 v6, v70, v10
	v_sub_f32_e32 v7, v7, v12
	v_mul_f32_e32 v10, v23, v13
	v_mul_f32_e32 v0, v6, v0
	v_lshlrev_b32_e32 v6, 16, v40
	v_fmac_f32_e32 v10, v19, v7
	v_mul_f32_e32 v0, v0, v6
	v_and_b32_e32 v6, 0xffff0000, v38
	v_add_f32_e32 v7, v70, v10
	v_sub_f32_e32 v8, v8, v12
	v_mul_f32_e32 v10, v24, v13
	v_mul_f32_e32 v6, v7, v6
	v_and_b32_e32 v7, 0xffff0000, v40
	v_fmac_f32_e32 v10, v20, v8
	v_mul_f32_e32 v6, v6, v7
	v_lshlrev_b32_e32 v7, 16, v39
	v_add_f32_e32 v8, v70, v10
	v_sub_f32_e32 v9, v9, v12
	v_mul_f32_e32 v10, v25, v13
	v_mul_f32_e32 v7, v8, v7
	v_lshlrev_b32_e32 v8, 16, v41
	v_fmac_f32_e32 v10, v21, v9
	v_mul_f32_e32 v7, v7, v8
	v_and_b32_e32 v8, 0xffff0000, v39
	v_add_f32_e32 v9, v70, v10
	v_mul_f32_e32 v8, v9, v8
	v_and_b32_e32 v9, 0xffff0000, v41
	v_or_b32_e32 v68, 0x70, v68
	v_mul_f32_e32 v8, v8, v9
	v_cvt_pk_bf16_f32 v6, v0, v6
	v_cvt_pk_bf16_f32 v7, v7, v8
	v_lshl_add_u32 v8, v68, 3, 0
	ds_read_b64 v[8:9], v8 offset:1024
	v_or_b32_e32 v0, s6, v85
	v_lshlrev_b32_e32 v0, 11, v0
	v_lshl_add_u64 v[10:11], v[66:67], 0, v[0:1]
	global_store_dwordx2 v[10:11], v[6:7], off
	s_waitcnt lgkmcnt(0)
	v_mul_f32_e32 v6, v22, v9
	s_nop 1
	v_sub_f32_e32 v2, v2, v8
	v_fmac_f32_e32 v6, v18, v2
	v_lshlrev_b32_e32 v0, 16, v34
	v_add_f32_e32 v2, v69, v6
	v_sub_f32_e32 v3, v3, v8
	v_mul_f32_e32 v6, v23, v9
	v_mul_f32_e32 v0, v2, v0
	v_lshlrev_b32_e32 v2, 16, v36
	v_fmac_f32_e32 v6, v19, v3
	v_mul_f32_e32 v0, v0, v2
	v_and_b32_e32 v2, 0xffff0000, v34
	v_add_f32_e32 v3, v69, v6
	v_sub_f32_e32 v4, v4, v8
	v_mul_f32_e32 v6, v24, v9
	v_mul_f32_e32 v2, v3, v2
	v_and_b32_e32 v3, 0xffff0000, v36
	v_fmac_f32_e32 v6, v20, v4
	v_mul_f32_e32 v2, v2, v3
	v_lshlrev_b32_e32 v3, 16, v35
	v_add_f32_e32 v4, v69, v6
	v_sub_f32_e32 v5, v5, v8
	v_mul_f32_e32 v6, v25, v9
	v_mul_f32_e32 v3, v4, v3
	v_lshlrev_b32_e32 v4, 16, v37
	v_fmac_f32_e32 v6, v21, v5
	v_mul_f32_e32 v3, v3, v4
	v_and_b32_e32 v4, 0xffff0000, v35
	v_add_f32_e32 v5, v69, v6
	v_mul_f32_e32 v4, v5, v4
	v_and_b32_e32 v5, 0xffff0000, v37
	v_cvt_pk_bf16_f32 v2, v0, v2
	v_or_b32_e32 v0, s6, v68
	v_mul_f32_e32 v4, v4, v5
	v_lshlrev_b32_e32 v0, 11, v0
	v_cvt_pk_bf16_f32 v3, v3, v4
	v_lshl_add_u64 v[4:5], v[66:67], 0, v[0:1]
	global_store_dwordx2 v[4:5], v[2:3], off
	s_barrier
